# v48 + HL hyena pass A loads de-serialised into 4 groups (re-test under the per-XCD longest-first queue)
# speedup vs baseline: 1.0090x; 1.0010x over previous
.LBB0_788:
	s_or_b64 exec, exec, s[36:37]
	s_lshr_b32 s21, s19, 6
	v_ashrrev_i32_e32 v23, 31, v22
	s_lshl_b32 s19, s21, 10
	v_lshlrev_b32_e32 v24, 14, v0
	v_add_u32_e32 v30, -1, v0
	s_addk_i32 s19, 0x1000
	v_and_b32_e32 v24, 0x4000, v24
	v_readlane_b32 s22, v251, 39
	v_lshl_add_u64 v[22:23], v[22:23], 2, s[26:27]
	v_med3_i32 v31, v30, 0, v202
	v_lshlrev_b32_e32 v25, 8, v125
	v_or_b32_e32 v130, s22, v24
	global_load_dword v100, v[22:23], off
	v_or_b32_e32 v22, s19, v31
	v_mov_b64_e32 v[106:107], s[6:7]
	v_and_b32_e32 v129, 0x3e00, v25
	v_add_u32_e32 v24, v121, v130
	s_mov_b32 s22, 0x20000
	v_mad_u64_u32 v[94:95], s[36:37], v22, s0, v[106:107]
	s_lshl_b32 s70, s23, 1
	v_add3_u32 v24, v24, v129, s22
	v_lshl_add_u64 v[22:23], v[94:95], 0, s[70:71]
	v_ashrrev_i32_e32 v25, 31, v24
	v_add_co_u32_e32 v26, vcc, s3, v22
	v_lshl_add_u64 v[24:25], v[24:25], 2, s[34:35]
	s_nop 0
	v_addc_co_u32_e32 v27, vcc, 0, v23, vcc
	global_load_dword v122, v[24:25], off
	s_nop 0
	global_load_dwordx4 v[22:25], v[26:27], off offset:1024
	s_nop 0
	global_load_dwordx4 v[26:29], v[26:27], off offset:3072
	v_cmp_eq_u32_e64 s[36:37], v30, v31
	v_med3_i32 v30, v0, 0, v202
	s_lshl_b32 s23, s23, 2
	s_add_u32 s84, s82, s23
	s_addc_u32 s85, s83, 0
	s_add_u32 s44, s84, 0x1000
	s_addc_u32 s45, s85, 0
	v_mov_b32_e32 v42, s23
	s_add_u32 s86, s80, s23
	s_addc_u32 s87, s81, 0
	v_lshlrev_b32_e32 v132, 1, v0
	v_add_u32_e32 v124, 0x100, v0
	v_add_u32_e32 v137, 0x101, v0
	v_med3_i32 v138, v137, 0, v202
	v_cmp_eq_u32_e64 s[60:61], v137, v138
	v_and_b32_e32 v127, 15, v0
	v_lshlrev_b32_e32 v131, 3, v125
	v_lshrrev_b32_e32 v128, 4, v125
	v_lshlrev_b32_e32 v160, 1, v131
	s_mov_b32 s22, 0
	s_mov_b64 s[90:91], -1
	s_mov_b64 s[92:93], 0
	s_waitcnt vmcnt(4)
	v_or_b32_e32 v174, s19, v30
	v_mad_u64_u32 v[96:97], s[38:39], v174, s0, v[106:107]
	v_lshl_add_u64 v[176:177], v[96:97], 0, s[70:71]
	v_add_co_u32_e32 v172, vcc, s3, v176
	s_nop 1
	v_addc_co_u32_e32 v173, vcc, 0, v177, vcc
	global_load_dwordx4 v[178:181], v[172:173], off offset:1024
	global_load_dwordx4 v[182:185], v[172:173], off offset:3072
	v_add_u32_e32 v174, 1, v0
	v_med3_i32 v31, v174, 0, v202
	v_or_b32_e32 v175, s19, v31
	v_mad_u64_u32 v[98:99], s[40:41], v175, s0, v[106:107]
	v_lshl_add_u64 v[176:177], v[98:99], 0, s[70:71]
	v_add_co_u32_e32 v172, vcc, s3, v176
	s_nop 1
	v_addc_co_u32_e32 v173, vcc, 0, v177, vcc
	global_load_dwordx4 v[204:207], v[172:173], off offset:1024
	global_load_dwordx4 v[208:211], v[172:173], off offset:3072
	global_load_dwordx4 v[172:175], v161, s[44:45] offset:16
	global_load_dwordx4 v[212:215], v195, s[84:85]
	global_load_dwordx4 v[216:219], v42, s[82:83] offset:16
	global_load_dwordx4 v[34:37], v42, s[82:83]
	global_load_dwordx4 v[38:41], v42, s[80:81] offset:16
	global_load_dwordx4 v[50:53], v42, s[80:81]
	s_add_u32 s44, s86, 0x1000
	s_addc_u32 s45, s87, 0
	global_load_dwordx4 v[220:223], v161, s[44:45] offset:16
	global_load_dwordx4 v[54:57], v195, s[86:87]
	s_add_u32 s44, s86, 0x1800
	s_addc_u32 s45, s87, 0
	global_load_dwordx4 v[224:227], v161, s[44:45] offset:16
	global_load_dwordx4 v[228:231], v195, s[86:87] offset:2048
	s_add_u32 s44, s86, 0x2800
	s_addc_u32 s45, s87, 0
	global_load_dwordx4 v[232:235], v161, s[44:45] offset:16
	global_load_dwordx4 v[70:73], v196, s[86:87] offset:2048
	s_add_u32 s44, s86, 0x3000
	s_addc_u32 s45, s87, 0
	global_load_dwordx4 v[236:239], v161, s[44:45] offset:16
	global_load_dwordx4 v[240:243], v197, s[86:87]
	s_add_u32 s44, s86, 0x4000
	s_addc_u32 s45, s87, 0
	global_load_dwordx4 v[244:247], v161, s[44:45] offset:16
	global_load_dwordx4 v[82:85], v198, s[86:87]
	s_waitcnt vmcnt(21)
	v_cndmask_b32_e64 v49, 0, v22, s[36:37]
	v_or_b32_e32 v22, s19, v30
	v_mad_u64_u32 v[96:97], s[38:39], v22, s0, v[106:107]
	v_cndmask_b32_e64 v48, 0, v23, s[36:37]
	s_nop 0
	s_waitcnt vmcnt(20)
	v_cndmask_b32_e64 v61, 0, v26, s[36:37]
	s_nop 0
	v_cndmask_b32_e64 v60, 0, v27, s[36:37]
	s_nop 0
	s_nop 0
	v_cndmask_b32_e64 v46, 0, v25, s[36:37]
	v_cndmask_b32_e64 v47, 0, v24, s[36:37]
	v_cndmask_b32_e64 v58, 0, v29, s[36:37]
	v_cndmask_b32_e64 v59, 0, v28, s[36:37]
	s_nop 0
	s_nop 0
	s_nop 0
	v_cmp_eq_u32_e64 s[38:39], v0, v30
	v_add_u32_e32 v30, 1, v0
	v_med3_i32 v31, v30, 0, v202
	v_lshlrev_b32_e32 v43, 16, v49
	v_and_b32_e32 v49, 0xffff0000, v49
	v_lshlrev_b32_e32 v66, 16, v61
	s_waitcnt vmcnt(19)
	v_cndmask_b32_e64 v65, 0, v178, s[38:39]
	v_or_b32_e32 v22, s19, v31
	v_mad_u64_u32 v[98:99], s[40:41], v22, s0, v[106:107]
	v_cndmask_b32_e64 v64, 0, v179, s[38:39]
	s_nop 0
	s_waitcnt vmcnt(18)
	v_cndmask_b32_e64 v77, 0, v182, s[38:39]
	s_nop 0
	v_cndmask_b32_e64 v76, 0, v183, s[38:39]
	s_nop 0
	s_nop 0
	v_cndmask_b32_e64 v62, 0, v181, s[38:39]
	v_cndmask_b32_e64 v63, 0, v180, s[38:39]
	v_cndmask_b32_e64 v74, 0, v185, s[38:39]
	v_cndmask_b32_e64 v75, 0, v184, s[38:39]
	s_nop 0
	s_nop 0
	s_nop 0
	v_cmp_eq_u32_e64 s[40:41], v30, v31
	v_lshlrev_b32_e32 v78, 16, v77
	s_waitcnt vmcnt(17)
	v_cndmask_b32_e64 v86, 0, v207, s[40:41]
	v_cndmask_b32_e64 v88, 0, v206, s[40:41]
	v_cndmask_b32_e64 v90, 0, v205, s[40:41]
	v_cndmask_b32_e64 v93, 0, v204, s[40:41]
	s_waitcnt vmcnt(16)
	v_cndmask_b32_e64 v87, 0, v211, s[40:41]
	v_cndmask_b32_e64 v89, 0, v210, s[40:41]
	v_cndmask_b32_e64 v91, 0, v209, s[40:41]
	v_cndmask_b32_e64 v101, 0, v208, s[40:41]
	s_nop 0
	s_nop 0
	s_nop 0
	s_nop 0
	s_nop 0
	s_nop 0
	s_nop 0
	s_nop 0
	v_lshlrev_b32_e32 v119, 16, v101
	s_waitcnt vmcnt(10)
	v_fma_f32 v92, v50, v43, v34
	s_nop 0
	s_nop 0
	v_fma_f32 v114, v51, v49, v35
	v_and_b32_e32 v49, 0xffff0000, v61
	s_nop 0
	s_nop 0
	s_waitcnt vmcnt(8)
	v_fma_f32 v117, v55, v49, v213
	v_lshlrev_b32_e32 v49, 16, v48
	v_and_b32_e32 v48, 0xffff0000, v48
	v_fma_f32 v110, v53, v48, v37
	v_and_b32_e32 v48, 0xffff0000, v60
	v_fma_f32 v115, v57, v48, v215
	v_lshlrev_b32_e32 v48, 16, v47
	v_and_b32_e32 v47, 0xffff0000, v47
	v_fma_f32 v104, v39, v47, v217
	v_and_b32_e32 v47, 0xffff0000, v59
	v_fma_f32 v111, v221, v47, v173
	v_lshlrev_b32_e32 v47, 16, v46
	v_and_b32_e32 v46, 0xffff0000, v46
	v_fma_f32 v112, v52, v49, v36
	v_lshlrev_b32_e32 v49, 16, v60
	v_fma_f32 v108, v38, v48, v216
	v_lshlrev_b32_e32 v48, 16, v59
	v_fma_f32 v103, v40, v47, v218
	v_lshlrev_b32_e32 v47, 16, v58
	v_fma_f32 v102, v41, v46, v219
	v_and_b32_e32 v46, 0xffff0000, v58
	v_fma_f32 v118, v54, v66, v212
	v_fma_f32 v116, v56, v49, v214
	v_fma_f32 v113, v220, v48, v172
	v_fma_f32 v109, v222, v47, v174
	v_fma_f32 v105, v223, v46, v175
	s_nop 0
	s_nop 0
	s_nop 0
	v_lshlrev_b32_e32 v58, 16, v65
	s_nop 0
	v_and_b32_e32 v65, 0xffff0000, v65
	s_waitcnt vmcnt(6)
	v_fmac_f32_e32 v92, v228, v58
	s_nop 0
	s_nop 0
	v_fmac_f32_e32 v114, v229, v65
	v_and_b32_e32 v65, 0xffff0000, v77
	s_nop 0
	s_nop 0
	s_waitcnt vmcnt(4)
	v_fmac_f32_e32 v117, v71, v65
	v_lshlrev_b32_e32 v65, 16, v64
	v_and_b32_e32 v64, 0xffff0000, v64
	v_fmac_f32_e32 v110, v231, v64
	v_and_b32_e32 v64, 0xffff0000, v76
	v_fmac_f32_e32 v115, v73, v64
	v_lshlrev_b32_e32 v64, 16, v63
	v_and_b32_e32 v63, 0xffff0000, v63
	v_fmac_f32_e32 v104, v225, v63
	v_and_b32_e32 v63, 0xffff0000, v75
	v_fmac_f32_e32 v111, v233, v63
	v_lshlrev_b32_e32 v63, 16, v62
	v_and_b32_e32 v62, 0xffff0000, v62
	v_fmac_f32_e32 v112, v230, v65
	v_lshlrev_b32_e32 v65, 16, v76
	v_fmac_f32_e32 v108, v224, v64
	v_lshlrev_b32_e32 v64, 16, v75
	v_fmac_f32_e32 v103, v226, v63
	v_lshlrev_b32_e32 v63, 16, v74
	v_fmac_f32_e32 v102, v227, v62
	v_and_b32_e32 v62, 0xffff0000, v74
	v_fmac_f32_e32 v118, v70, v78
	v_fmac_f32_e32 v116, v72, v65
	v_fmac_f32_e32 v113, v232, v64
	v_fmac_f32_e32 v109, v234, v63
	v_fmac_f32_e32 v105, v235, v62
	s_nop 0
	s_nop 0
	s_nop 0
	v_lshlrev_b32_e32 v74, 16, v93
	s_nop 0
	v_and_b32_e32 v93, 0xffff0000, v93
	s_waitcnt vmcnt(2)
	v_fmac_f32_e32 v92, v240, v74
	s_nop 0
	s_nop 0
	v_fmac_f32_e32 v114, v241, v93
	v_and_b32_e32 v93, 0xffff0000, v101
	v_add_u32_e32 v101, s17, v132
	s_waitcnt vmcnt(0)
	v_fmac_f32_e32 v117, v83, v93
	s_waitcnt vmcnt(0)
	v_add_u32_e32 v248, 0xff, v0
	v_med3_i32 v249, v248, 0, v202
	v_or_b32_e32 v250, s19, v249
	v_mad_u64_u32 v[42:43], s[44:45], v250, s0, v[106:107]
	v_lshl_add_u64 v[44:45], v[42:43], 0, s[70:71]
	v_add_co_u32_e32 v158, vcc, s3, v44
	s_nop 1
	v_addc_co_u32_e32 v159, vcc, 0, v45, vcc
	global_load_dwordx4 v[46:49], v[158:159], off offset:1024
	global_load_dwordx4 v[58:61], v[158:159], off offset:3072
	v_med3_i32 v248, v124, 0, v202
	v_or_b32_e32 v249, s19, v248
	v_mad_u64_u32 v[42:43], s[44:45], v249, s0, v[106:107]
	v_lshl_add_u64 v[44:45], v[42:43], 0, s[70:71]
	v_add_co_u32_e32 v158, vcc, s3, v44
	s_nop 1
	v_addc_co_u32_e32 v159, vcc, 0, v45, vcc
	global_load_dwordx4 v[62:65], v[158:159], off offset:1024
	global_load_dwordx4 v[66:69], v[158:159], off offset:3072
	v_or_b32_e32 v248, s19, v138
	v_mad_u64_u32 v[42:43], s[44:45], v248, s0, v[106:107]
	v_lshl_add_u64 v[44:45], v[42:43], 0, s[70:71]
	v_add_co_u32_e32 v158, vcc, s3, v44
	s_nop 1
	v_addc_co_u32_e32 v159, vcc, 0, v45, vcc
	global_load_dwordx4 v[74:77], v[158:159], off offset:1024
	global_load_dwordx4 v[78:81], v[158:159], off offset:3072
	v_add_u32_e32 v248, 0x1ff, v0
	v_med3_i32 v249, v248, 0, v202
	v_or_b32_e32 v250, s19, v249
	v_mad_u64_u32 v[42:43], s[44:45], v250, s0, v[106:107]
	v_lshl_add_u64 v[44:45], v[42:43], 0, s[70:71]
	v_add_co_u32_e32 v158, vcc, s3, v44
	s_nop 1
	v_addc_co_u32_e32 v159, vcc, 0, v45, vcc
	global_load_dwordx4 v[154:157], v[158:159], off offset:1024
	global_load_dwordx4 v[176:179], v[158:159], off offset:3072
	v_add_u32_e32 v248, 0x200, v0
	v_med3_i32 v249, v248, 0, v202
	v_or_b32_e32 v250, s19, v249
	v_mad_u64_u32 v[42:43], s[44:45], v250, s0, v[106:107]
	v_lshl_add_u64 v[44:45], v[42:43], 0, s[70:71]
	v_add_co_u32_e32 v158, vcc, s3, v44
	s_nop 1
	v_addc_co_u32_e32 v159, vcc, 0, v45, vcc
	global_load_dwordx4 v[180:183], v[158:159], off offset:1024
	global_load_dwordx4 v[184:187], v[158:159], off offset:3072
	v_add_u32_e32 v248, 0x201, v0
	v_med3_i32 v249, v248, 0, v202
	v_or_b32_e32 v250, s19, v249
	v_mad_u64_u32 v[42:43], s[44:45], v250, s0, v[106:107]
	v_lshl_add_u64 v[44:45], v[42:43], 0, s[70:71]
	v_add_co_u32_e32 v158, vcc, s3, v44
	s_nop 1
	v_addc_co_u32_e32 v159, vcc, 0, v45, vcc
	global_load_dwordx4 v[204:207], v[158:159], off offset:1024
	global_load_dwordx4 v[208:211], v[158:159], off offset:3072
	v_lshlrev_b32_e32 v93, 16, v90
	v_and_b32_e32 v90, 0xffff0000, v90
	v_fmac_f32_e32 v110, v243, v90
	v_and_b32_e32 v90, 0xffff0000, v91
	v_fmac_f32_e32 v115, v85, v90
	v_lshlrev_b32_e32 v90, 16, v88
	v_and_b32_e32 v88, 0xffff0000, v88
	v_fmac_f32_e32 v104, v237, v88
	v_and_b32_e32 v88, 0xffff0000, v89
	v_fmac_f32_e32 v111, v245, v88
	v_lshlrev_b32_e32 v88, 16, v86
	v_and_b32_e32 v86, 0xffff0000, v86
	v_fmac_f32_e32 v118, v82, v119
	v_fmac_f32_e32 v102, v239, v86
	v_and_b32_e32 v86, 0xffff0000, v87
	v_fmac_f32_e32 v105, v247, v86
	v_bfe_u32 v86, v118, 16, 1
	v_add3_u32 v86, v118, v86, s94
	ds_write_b16_d16_hi v101, v86 offset:512
	v_bfe_u32 v86, v92, 16, 1
	v_add3_u32 v86, v92, v86, s94
	ds_write_b16_d16_hi v101, v86 offset:24576
	v_bfe_u32 v86, v117, 16, 1
	v_add3_u32 v86, v117, v86, s94
	v_fmac_f32_e32 v112, v242, v93
	v_lshlrev_b32_e32 v93, 16, v91
	ds_write_b16_d16_hi v101, v86 offset:3584
	v_bfe_u32 v86, v114, 16, 1
	v_fmac_f32_e32 v116, v84, v93
	v_add3_u32 v86, v114, v86, s94
	ds_write_b16_d16_hi v101, v86 offset:26624
	v_bfe_u32 v86, v116, 16, 1
	v_add3_u32 v86, v116, v86, s94
	ds_write_b16_d16_hi v101, v86 offset:6656
	v_bfe_u32 v86, v112, 16, 1
	v_add3_u32 v86, v112, v86, s94
	ds_write_b16_d16_hi v101, v86 offset:28672
	v_bfe_u32 v86, v115, 16, 1
	v_add3_u32 v86, v115, v86, s94
	v_fmac_f32_e32 v108, v236, v90
	v_lshlrev_b32_e32 v90, 16, v89
	ds_write_b16_d16_hi v101, v86 offset:9728
	v_bfe_u32 v86, v110, 16, 1
	v_fmac_f32_e32 v113, v244, v90
	v_add3_u32 v86, v110, v86, s94
	ds_write_b16_d16_hi v101, v86 offset:30720
	v_bfe_u32 v86, v113, 16, 1
	v_add3_u32 v86, v113, v86, s94
	ds_write_b16_d16_hi v101, v86 offset:12800
	v_bfe_u32 v86, v108, 16, 1
	v_add3_u32 v86, v108, v86, s94
	ds_write_b16_d16_hi v101, v86 offset:32768
	v_bfe_u32 v86, v111, 16, 1
	v_add3_u32 v86, v111, v86, s94
	v_fmac_f32_e32 v103, v238, v88
	v_lshlrev_b32_e32 v88, 16, v87
	ds_write_b16_d16_hi v101, v86 offset:15872
	v_bfe_u32 v86, v104, 16, 1
	v_fmac_f32_e32 v109, v246, v88
	v_add3_u32 v86, v104, v86, s94
	ds_write_b16_d16_hi v101, v86 offset:34816
	v_bfe_u32 v86, v109, 16, 1
	v_add3_u32 v86, v109, v86, s94
	ds_write_b16_d16_hi v101, v86 offset:18944
	v_bfe_u32 v86, v103, 16, 1
	v_add3_u32 v86, v103, v86, s94
	ds_write_b16_d16_hi v101, v86 offset:36864
	v_bfe_u32 v86, v105, 16, 1
	v_add3_u32 v86, v105, v86, s94
	ds_write_b16_d16_hi v101, v86 offset:22016
	v_bfe_u32 v86, v102, 16, 1
	v_add3_u32 v86, v102, v86, s94
	v_add_u32_e32 v102, 0xff, v0
	v_med3_i32 v103, v102, 0, v202
	ds_write_b16_d16_hi v101, v86 offset:38912
	v_or_b32_e32 v86, s19, v103
	v_mad_u64_u32 v[110:111], s[44:45], v86, s0, v[106:107]
	s_nop 0
	s_nop 0
	v_cmp_eq_u32_e64 s[50:51], v102, v103
	s_nop 0
	s_nop 0
	s_nop 0
	s_nop 0
	s_nop 0
	v_med3_i32 v116, v124, 0, v202
	v_cmp_eq_u32_e64 s[56:57], v124, v116
	s_waitcnt vmcnt(11)
	v_cndmask_b32_e64 v105, 0, v46, s[50:51]
	v_or_b32_e32 v86, s19, v116
	v_mad_u64_u32 v[114:115], s[44:45], v86, s0, v[106:107]
	v_cndmask_b32_e64 v104, 0, v47, s[50:51]
	s_nop 0
	s_waitcnt vmcnt(10)
	v_cndmask_b32_e64 v113, 0, v58, s[50:51]
	s_nop 0
	v_cndmask_b32_e64 v112, 0, v59, s[50:51]
	s_nop 0
	s_nop 0
	v_cndmask_b32_e64 v102, 0, v49, s[50:51]
	v_cndmask_b32_e64 v103, 0, v48, s[50:51]
	v_cndmask_b32_e64 v108, 0, v61, s[50:51]
	v_cndmask_b32_e64 v109, 0, v60, s[50:51]
	s_nop 0
	s_nop 0
	s_nop 0
	v_lshlrev_b32_e32 v137, 16, v105
	v_and_b32_e32 v105, 0xffff0000, v105
	v_fma_f32 v105, v51, v105, v35
	v_lshlrev_b32_e32 v139, 16, v104
	v_and_b32_e32 v104, 0xffff0000, v104
	v_lshlrev_b32_e32 v140, 16, v112
	v_fma_f32 v104, v53, v104, v37
	v_and_b32_e32 v112, 0xffff0000, v112
	v_fma_f32 v112, v57, v112, v215
	v_lshlrev_b32_e32 v141, 16, v103
	v_and_b32_e32 v103, 0xffff0000, v103
	v_lshlrev_b32_e32 v142, 16, v109
	v_fma_f32 v103, v39, v103, v217
	v_and_b32_e32 v109, 0xffff0000, v109
	v_fma_f32 v109, v221, v109, v173
	v_lshlrev_b32_e32 v143, 16, v102
	v_and_b32_e32 v102, 0xffff0000, v102
	v_lshlrev_b32_e32 v144, 16, v108
	v_fma_f32 v102, v41, v102, v219
	v_and_b32_e32 v108, 0xffff0000, v108
	v_fma_f32 v108, v223, v108, v175
	v_fma_f32 v139, v52, v139, v36
	v_fma_f32 v140, v56, v140, v214
	v_fma_f32 v141, v38, v141, v216
	v_fma_f32 v142, v220, v142, v172
	v_fma_f32 v143, v40, v143, v218
	v_fma_f32 v137, v50, v137, v34
	v_fma_f32 v144, v222, v144, v174
	s_waitcnt vmcnt(9)
	v_cndmask_b32_e64 v123, 0, v62, s[56:57]
	v_or_b32_e32 v86, s19, v138
	v_mad_u64_u32 v[118:119], s[44:45], v86, s0, v[106:107]
	v_cndmask_b32_e64 v120, 0, v63, s[56:57]
	s_nop 0
	s_waitcnt vmcnt(8)
	v_cndmask_b32_e64 v136, 0, v66, s[56:57]
	s_nop 0
	v_cndmask_b32_e64 v135, 0, v67, s[56:57]
	s_nop 0
	s_nop 0
	v_cndmask_b32_e64 v116, 0, v65, s[56:57]
	v_cndmask_b32_e64 v117, 0, v64, s[56:57]
	v_cndmask_b32_e64 v133, 0, v69, s[56:57]
	v_cndmask_b32_e64 v134, 0, v68, s[56:57]
	s_nop 0
	s_nop 0
	s_nop 0
	v_lshlrev_b32_e32 v138, 16, v113
	v_and_b32_e32 v113, 0xffff0000, v113
	v_lshlrev_b32_e32 v145, 16, v123
	v_and_b32_e32 v123, 0xffff0000, v123
	v_fma_f32 v113, v55, v113, v213
	v_fmac_f32_e32 v105, v229, v123
	v_and_b32_e32 v123, 0xffff0000, v136
	v_fmac_f32_e32 v113, v71, v123
	v_lshlrev_b32_e32 v123, 16, v120
	v_and_b32_e32 v120, 0xffff0000, v120
	v_fmac_f32_e32 v104, v231, v120
	v_and_b32_e32 v120, 0xffff0000, v135
	v_fmac_f32_e32 v112, v73, v120
	v_lshlrev_b32_e32 v120, 16, v117
	v_and_b32_e32 v117, 0xffff0000, v117
	v_fmac_f32_e32 v103, v225, v117
	v_and_b32_e32 v117, 0xffff0000, v134
	v_fmac_f32_e32 v109, v233, v117
	v_lshlrev_b32_e32 v117, 16, v116
	v_and_b32_e32 v116, 0xffff0000, v116
	s_waitcnt vmcnt(8)
	v_add_u32_e32 v248, 0x2ff, v0
	v_med3_i32 v249, v248, 0, v202
	v_or_b32_e32 v250, s19, v249
	v_mad_u64_u32 v[42:43], s[100:101], v250, s0, v[106:107]
	v_lshl_add_u64 v[44:45], v[42:43], 0, s[70:71]
	v_add_co_u32_e32 v158, vcc, s3, v44
	s_nop 1
	v_addc_co_u32_e32 v159, vcc, 0, v45, vcc
	global_load_dwordx4 v[46:49], v[158:159], off offset:1024
	global_load_dwordx4 v[58:61], v[158:159], off offset:3072
	v_add_u32_e32 v248, 0x300, v0
	v_med3_i32 v249, v248, 0, v202
	v_or_b32_e32 v250, s19, v249
	v_mad_u64_u32 v[42:43], s[46:47], v250, s0, v[106:107]
	v_lshl_add_u64 v[44:45], v[42:43], 0, s[70:71]
	v_add_co_u32_e32 v158, vcc, s3, v44
	s_nop 1
	v_addc_co_u32_e32 v159, vcc, 0, v45, vcc
	global_load_dwordx4 v[62:65], v[158:159], off offset:1024
	global_load_dwordx4 v[66:69], v[158:159], off offset:3072
	v_fmac_f32_e32 v102, v227, v116
	v_and_b32_e32 v116, 0xffff0000, v133
	v_fmac_f32_e32 v108, v235, v116
	v_fmac_f32_e32 v139, v230, v123
	v_lshlrev_b32_e32 v123, 16, v135
	v_fmac_f32_e32 v140, v72, v123
	v_fmac_f32_e32 v141, v224, v120
	v_lshlrev_b32_e32 v120, 16, v134
	v_fmac_f32_e32 v142, v232, v120
	v_fmac_f32_e32 v143, v226, v117
	v_lshlrev_b32_e32 v117, 16, v133
	v_fma_f32 v138, v54, v138, v212
	v_fmac_f32_e32 v137, v228, v145
	v_lshlrev_b32_e32 v145, 16, v136
	v_fmac_f32_e32 v144, v234, v117
	v_fmac_f32_e32 v138, v70, v145
	v_add_u32_e32 v123, 0x200, v0
	s_waitcnt vmcnt(11)
	v_cndmask_b32_e64 v86, 0, v74, s[60:61]
	s_waitcnt vmcnt(10)
	v_cndmask_b32_e64 v90, 0, v78, s[60:61]
	v_lshlrev_b32_e32 v116, 16, v86
	v_and_b32_e32 v86, 0xffff0000, v86
	v_cndmask_b32_e64 v87, 0, v75, s[60:61]
	v_fmac_f32_e32 v105, v241, v86
	v_and_b32_e32 v86, 0xffff0000, v90
	v_cndmask_b32_e64 v91, 0, v79, s[60:61]
	v_fmac_f32_e32 v113, v83, v86
	v_lshlrev_b32_e32 v86, 16, v87
	v_fmac_f32_e32 v139, v242, v86
	v_lshlrev_b32_e32 v86, 16, v91
	v_fmac_f32_e32 v140, v84, v86
	v_and_b32_e32 v86, 0xffff0000, v87
	v_cndmask_b32_e64 v88, 0, v76, s[60:61]
	v_fmac_f32_e32 v104, v243, v86
	v_and_b32_e32 v86, 0xffff0000, v91
	v_cndmask_b32_e64 v92, 0, v80, s[60:61]
	v_fmac_f32_e32 v112, v85, v86
	v_lshlrev_b32_e32 v86, 16, v88
	v_fmac_f32_e32 v141, v236, v86
	v_lshlrev_b32_e32 v86, 16, v92
	v_fmac_f32_e32 v142, v244, v86
	v_and_b32_e32 v86, 0xffff0000, v88
	v_cndmask_b32_e64 v89, 0, v77, s[60:61]
	v_fmac_f32_e32 v103, v237, v86
	v_and_b32_e32 v86, 0xffff0000, v92
	v_cndmask_b32_e64 v93, 0, v81, s[60:61]
	v_fmac_f32_e32 v109, v245, v86
	v_lshlrev_b32_e32 v86, 16, v89
	v_fmac_f32_e32 v143, v238, v86
	v_lshlrev_b32_e32 v86, 16, v93
	v_fmac_f32_e32 v137, v240, v116
	v_lshlrev_b32_e32 v116, 16, v90
	v_fmac_f32_e32 v144, v246, v86
	v_and_b32_e32 v86, 0xffff0000, v89
	v_fmac_f32_e32 v138, v82, v116
	v_fmac_f32_e32 v102, v239, v86
	v_and_b32_e32 v86, 0xffff0000, v93
	v_fmac_f32_e32 v108, v247, v86
	v_bfe_u32 v86, v138, 16, 1
	v_add3_u32 v86, v138, v86, s94
	s_waitcnt vmcnt(10)
	v_add_u32_e32 v248, 0x301, v0
	v_med3_i32 v249, v248, 0, v202
	v_or_b32_e32 v250, s19, v249
	v_mad_u64_u32 v[42:43], s[52:53], v250, s0, v[106:107]
	v_lshl_add_u64 v[44:45], v[42:43], 0, s[70:71]
	v_add_co_u32_e32 v158, vcc, s3, v44
	s_nop 1
	v_addc_co_u32_e32 v159, vcc, 0, v45, vcc
	global_load_dwordx4 v[74:77], v[158:159], off offset:1024
	global_load_dwordx4 v[78:81], v[158:159], off offset:3072
	ds_write_b16_d16_hi v101, v86 offset:1024
	v_bfe_u32 v86, v137, 16, 1
	v_add3_u32 v86, v137, v86, s94
	ds_write_b16_d16_hi v101, v86 offset:25088
	v_bfe_u32 v86, v113, 16, 1
	v_add3_u32 v86, v113, v86, s94
	ds_write_b16_d16_hi v101, v86 offset:4096
	v_bfe_u32 v86, v105, 16, 1
	v_add3_u32 v86, v105, v86, s94
	ds_write_b16_d16_hi v101, v86 offset:27136
	v_bfe_u32 v86, v140, 16, 1
	v_add3_u32 v86, v140, v86, s94
	ds_write_b16_d16_hi v101, v86 offset:7168
	v_bfe_u32 v86, v139, 16, 1
	v_add3_u32 v86, v139, v86, s94
	ds_write_b16_d16_hi v101, v86 offset:29184
	v_bfe_u32 v86, v112, 16, 1
	v_add3_u32 v86, v112, v86, s94
	ds_write_b16_d16_hi v101, v86 offset:10240
	v_bfe_u32 v86, v104, 16, 1
	v_add3_u32 v86, v104, v86, s94
	ds_write_b16_d16_hi v101, v86 offset:31232
	v_bfe_u32 v86, v142, 16, 1
	v_add3_u32 v86, v142, v86, s94
	ds_write_b16_d16_hi v101, v86 offset:13312
	v_bfe_u32 v86, v141, 16, 1
	v_add3_u32 v86, v141, v86, s94
	ds_write_b16_d16_hi v101, v86 offset:33280
	v_bfe_u32 v86, v109, 16, 1
	v_add3_u32 v86, v109, v86, s94
	ds_write_b16_d16_hi v101, v86 offset:16384
	v_bfe_u32 v86, v103, 16, 1
	v_add3_u32 v86, v103, v86, s94
	ds_write_b16_d16_hi v101, v86 offset:35328
	v_bfe_u32 v86, v144, 16, 1
	v_add3_u32 v86, v144, v86, s94
	ds_write_b16_d16_hi v101, v86 offset:19456
	v_bfe_u32 v86, v143, 16, 1
	v_add3_u32 v86, v143, v86, s94
	ds_write_b16_d16_hi v101, v86 offset:37376
	v_bfe_u32 v86, v108, 16, 1
	v_add3_u32 v86, v108, v86, s94
	ds_write_b16_d16_hi v101, v86 offset:22528
	v_bfe_u32 v86, v102, 16, 1
	v_add3_u32 v86, v102, v86, s94
	v_add_u32_e32 v102, 0x1ff, v0
	v_med3_i32 v103, v102, 0, v202
	ds_write_b16_d16_hi v101, v86 offset:39424
	v_or_b32_e32 v86, s19, v103
	v_mad_u64_u32 v[108:109], s[44:45], v86, s0, v[106:107]
	s_nop 0
	s_nop 0
	v_cmp_eq_u32_e64 s[48:49], v102, v103
	s_nop 0
	s_nop 0
	s_nop 0
	s_nop 0
	s_nop 0
	v_med3_i32 v116, v123, 0, v202
	v_add_u32_e32 v144, 0x201, v0
	v_cmp_eq_u32_e64 s[54:55], v123, v116
	v_med3_i32 v145, v144, 0, v202
	v_cmp_eq_u32_e64 s[58:59], v144, v145
	s_waitcnt vmcnt(11)
	v_cndmask_b32_e64 v105, 0, v154, s[48:49]
	v_or_b32_e32 v86, s19, v116
	v_mad_u64_u32 v[112:113], s[44:45], v86, s0, v[106:107]
	v_cndmask_b32_e64 v104, 0, v155, s[48:49]
	s_nop 0
	s_waitcnt vmcnt(10)
	v_cndmask_b32_e64 v135, 0, v176, s[48:49]
	s_nop 0
	v_cndmask_b32_e64 v134, 0, v177, s[48:49]
	s_nop 0
	s_nop 0
	v_cndmask_b32_e64 v102, 0, v157, s[48:49]
	v_cndmask_b32_e64 v103, 0, v156, s[48:49]
	v_cndmask_b32_e64 v120, 0, v179, s[48:49]
	v_cndmask_b32_e64 v133, 0, v178, s[48:49]
	s_nop 0
	s_nop 0
	s_nop 0
	v_lshlrev_b32_e32 v144, 16, v105
	v_lshlrev_b32_e32 v152, 16, v120
	v_and_b32_e32 v120, 0xffff0000, v120
	v_fma_f32 v144, v50, v144, v34
	v_fma_f32 v153, v223, v120, v175
	v_and_b32_e32 v105, 0xffff0000, v105
	v_fma_f32 v105, v51, v105, v35
	v_lshlrev_b32_e32 v146, 16, v104
	v_fma_f32 v146, v52, v146, v36
	v_lshlrev_b32_e32 v147, 16, v134
	v_fma_f32 v147, v56, v147, v214
	v_and_b32_e32 v104, 0xffff0000, v104
	v_fma_f32 v104, v53, v104, v37
	v_and_b32_e32 v134, 0xffff0000, v134
	v_fma_f32 v134, v57, v134, v215
	v_lshlrev_b32_e32 v148, 16, v103
	v_fma_f32 v148, v38, v148, v216
	v_lshlrev_b32_e32 v149, 16, v133
	v_fma_f32 v149, v220, v149, v172
	v_and_b32_e32 v103, 0xffff0000, v103
	v_fma_f32 v103, v39, v103, v217
	v_and_b32_e32 v133, 0xffff0000, v133
	v_fma_f32 v133, v221, v133, v173
	v_lshlrev_b32_e32 v151, 16, v102
	v_fma_f32 v151, v40, v151, v218
	v_fma_f32 v152, v222, v152, v174
	v_and_b32_e32 v102, 0xffff0000, v102
	v_fma_f32 v102, v41, v102, v219
	s_waitcnt vmcnt(9)
	v_cndmask_b32_e64 v139, 0, v180, s[54:55]
	v_or_b32_e32 v86, s19, v145
	v_mad_u64_u32 v[116:117], s[44:45], v86, s0, v[106:107]
	v_cndmask_b32_e64 v138, 0, v181, s[54:55]
	s_nop 0
	s_waitcnt vmcnt(8)
	v_cndmask_b32_e64 v143, 0, v184, s[54:55]
	s_nop 0
	v_cndmask_b32_e64 v142, 0, v185, s[54:55]
	s_nop 0
	s_nop 0
	v_cndmask_b32_e64 v136, 0, v183, s[54:55]
	v_cndmask_b32_e64 v137, 0, v182, s[54:55]
	v_cndmask_b32_e64 v140, 0, v187, s[54:55]
	v_cndmask_b32_e64 v141, 0, v186, s[54:55]
	s_nop 0
	s_nop 0
	s_nop 0
	v_lshlrev_b32_e32 v145, 16, v135
	v_lshlrev_b32_e32 v120, 16, v139
	v_fma_f32 v145, v54, v145, v212
	v_fmac_f32_e32 v144, v228, v120
	v_lshlrev_b32_e32 v120, 16, v143
	v_and_b32_e32 v135, 0xffff0000, v135
	v_fmac_f32_e32 v145, v70, v120
	v_and_b32_e32 v120, 0xffff0000, v139
	v_fma_f32 v135, v55, v135, v213
	v_fmac_f32_e32 v105, v229, v120
	v_and_b32_e32 v120, 0xffff0000, v143
	v_fmac_f32_e32 v135, v71, v120
	v_lshlrev_b32_e32 v120, 16, v138
	v_fmac_f32_e32 v146, v230, v120
	v_lshlrev_b32_e32 v120, 16, v142
	v_fmac_f32_e32 v147, v72, v120
	v_and_b32_e32 v120, 0xffff0000, v138
	v_fmac_f32_e32 v104, v231, v120
	v_and_b32_e32 v120, 0xffff0000, v142
	v_fmac_f32_e32 v134, v73, v120
	v_lshlrev_b32_e32 v120, 16, v137
	v_fmac_f32_e32 v148, v224, v120
	v_lshlrev_b32_e32 v120, 16, v141
	v_fmac_f32_e32 v149, v232, v120
	v_and_b32_e32 v120, 0xffff0000, v137
	v_fmac_f32_e32 v103, v225, v120
	v_and_b32_e32 v120, 0xffff0000, v141
	v_fmac_f32_e32 v133, v233, v120
	v_lshlrev_b32_e32 v120, 16, v136
	v_fmac_f32_e32 v151, v226, v120
	v_lshlrev_b32_e32 v120, 16, v140
	v_fmac_f32_e32 v152, v234, v120
	v_and_b32_e32 v120, 0xffff0000, v136
	v_fmac_f32_e32 v102, v227, v120
	v_and_b32_e32 v120, 0xffff0000, v140
	v_fmac_f32_e32 v153, v235, v120
	s_waitcnt vmcnt(7)
	v_cndmask_b32_e64 v86, 0, v204, s[58:59]
	s_waitcnt vmcnt(6)
	v_cndmask_b32_e64 v90, 0, v208, s[58:59]
	v_lshlrev_b32_e32 v120, 16, v86
	v_and_b32_e32 v86, 0xffff0000, v86
	v_cndmask_b32_e64 v87, 0, v205, s[58:59]
	v_fmac_f32_e32 v105, v241, v86
	v_and_b32_e32 v86, 0xffff0000, v90
	v_cndmask_b32_e64 v91, 0, v209, s[58:59]
	v_fmac_f32_e32 v135, v83, v86
	v_lshlrev_b32_e32 v86, 16, v87
	v_fmac_f32_e32 v146, v242, v86
	v_lshlrev_b32_e32 v86, 16, v91
	v_fmac_f32_e32 v147, v84, v86
	v_and_b32_e32 v86, 0xffff0000, v87
	v_cndmask_b32_e64 v88, 0, v206, s[58:59]
	v_fmac_f32_e32 v104, v243, v86
	v_and_b32_e32 v86, 0xffff0000, v91
	v_cndmask_b32_e64 v92, 0, v210, s[58:59]
	v_fmac_f32_e32 v134, v85, v86
	v_lshlrev_b32_e32 v86, 16, v88
	v_fmac_f32_e32 v148, v236, v86
	v_lshlrev_b32_e32 v86, 16, v92
	v_fmac_f32_e32 v149, v244, v86
	v_and_b32_e32 v86, 0xffff0000, v88
	v_cndmask_b32_e64 v89, 0, v207, s[58:59]
	v_fmac_f32_e32 v103, v237, v86
	v_and_b32_e32 v86, 0xffff0000, v92
	v_cndmask_b32_e64 v93, 0, v211, s[58:59]
	v_fmac_f32_e32 v133, v245, v86
	v_lshlrev_b32_e32 v86, 16, v89
	v_fmac_f32_e32 v151, v238, v86
	v_lshlrev_b32_e32 v86, 16, v93
	v_fmac_f32_e32 v144, v240, v120
	v_lshlrev_b32_e32 v120, 16, v90
	v_fmac_f32_e32 v152, v246, v86
	v_and_b32_e32 v86, 0xffff0000, v89
	v_fmac_f32_e32 v145, v82, v120
	v_fmac_f32_e32 v102, v239, v86
	v_and_b32_e32 v86, 0xffff0000, v93
	v_fmac_f32_e32 v153, v247, v86
	v_bfe_u32 v86, v145, 16, 1
	v_add3_u32 v86, v145, v86, s94
	ds_write_b16_d16_hi v101, v86 offset:1536
	v_bfe_u32 v86, v144, 16, 1
	v_add3_u32 v86, v144, v86, s94
	ds_write_b16_d16_hi v101, v86 offset:25600
	v_bfe_u32 v86, v135, 16, 1
	v_add3_u32 v86, v135, v86, s94
	ds_write_b16_d16_hi v101, v86 offset:4608
	v_bfe_u32 v86, v105, 16, 1
	v_add3_u32 v86, v105, v86, s94
	ds_write_b16_d16_hi v101, v86 offset:27648
	v_bfe_u32 v86, v147, 16, 1
	v_add3_u32 v86, v147, v86, s94
	ds_write_b16_d16_hi v101, v86 offset:7680
	v_bfe_u32 v86, v146, 16, 1
	v_add3_u32 v86, v146, v86, s94
	ds_write_b16_d16_hi v101, v86 offset:29696
	v_bfe_u32 v86, v134, 16, 1
	v_add3_u32 v86, v134, v86, s94
	ds_write_b16_d16_hi v101, v86 offset:10752
	v_bfe_u32 v86, v104, 16, 1
	v_add3_u32 v86, v104, v86, s94
	ds_write_b16_d16_hi v101, v86 offset:31744
	v_bfe_u32 v86, v149, 16, 1
	v_add3_u32 v86, v149, v86, s94
	ds_write_b16_d16_hi v101, v86 offset:13824
	v_bfe_u32 v86, v148, 16, 1
	v_add3_u32 v86, v148, v86, s94
	ds_write_b16_d16_hi v101, v86 offset:33792
	v_bfe_u32 v86, v133, 16, 1
	v_add3_u32 v86, v133, v86, s94
	ds_write_b16_d16_hi v101, v86 offset:16896
	v_bfe_u32 v86, v103, 16, 1
	v_add3_u32 v86, v103, v86, s94
	ds_write_b16_d16_hi v101, v86 offset:35840
	v_bfe_u32 v86, v152, 16, 1
	v_add3_u32 v86, v152, v86, s94
	ds_write_b16_d16_hi v101, v86 offset:19968
	v_bfe_u32 v86, v151, 16, 1
	v_add3_u32 v86, v151, v86, s94
	ds_write_b16_d16_hi v101, v86 offset:37888
	v_bfe_u32 v86, v153, 16, 1
	v_add3_u32 v86, v153, v86, s94
	ds_write_b16_d16_hi v101, v86 offset:23040
	v_bfe_u32 v86, v102, 16, 1
	v_add_u32_e32 v104, 0x2ff, v0
	v_add3_u32 v86, v102, v86, s94
	v_med3_i32 v105, v104, 0, v202
	ds_write_b16_d16_hi v101, v86 offset:39936
	v_or_b32_e32 v86, s19, v105
	v_mad_u64_u32 v[102:103], s[44:45], v86, s0, v[106:107]
	s_nop 0
	s_nop 0
	v_add_u32_e32 v120, 0x300, v0
	s_nop 0
	s_nop 0
	s_nop 0
	s_nop 0
	s_nop 0
	v_cmp_eq_u32_e64 s[44:45], v104, v105
	v_med3_i32 v141, v120, 0, v202
	v_add_u32_e32 v149, 0x301, v0
	v_med3_i32 v151, v149, 0, v202
	s_waitcnt vmcnt(5)
	v_cndmask_b32_e64 v136, 0, v46, s[44:45]
	v_or_b32_e32 v86, s19, v141
	v_mad_u64_u32 v[104:105], s[46:47], v86, s0, v[106:107]
	v_cndmask_b32_e64 v135, 0, v47, s[44:45]
	s_nop 0
	s_waitcnt vmcnt(4)
	v_cndmask_b32_e64 v140, 0, v58, s[44:45]
	s_nop 0
	v_cndmask_b32_e64 v139, 0, v59, s[44:45]
	s_nop 0
	s_nop 0
	v_cndmask_b32_e64 v133, 0, v49, s[44:45]
	v_cndmask_b32_e64 v134, 0, v48, s[44:45]
	v_cndmask_b32_e64 v137, 0, v61, s[44:45]
	v_cndmask_b32_e64 v138, 0, v60, s[44:45]
	s_nop 0
	s_nop 0
	s_nop 0
	v_cmp_eq_u32_e64 s[46:47], v120, v141
	s_nop 0
	s_waitcnt vmcnt(3)
	v_cndmask_b32_e64 v144, 0, v62, s[46:47]
	v_or_b32_e32 v86, s19, v151
	v_mad_u64_u32 v[106:107], s[52:53], v86, s0, v[106:107]
	v_cndmask_b32_e64 v143, 0, v63, s[46:47]
	s_nop 0
	s_waitcnt vmcnt(2)
	v_cndmask_b32_e64 v148, 0, v66, s[46:47]
	s_nop 0
	v_cndmask_b32_e64 v147, 0, v67, s[46:47]
	s_nop 0
	s_nop 0
	v_cndmask_b32_e64 v141, 0, v65, s[46:47]
	v_cndmask_b32_e64 v142, 0, v64, s[46:47]
	v_cndmask_b32_e64 v145, 0, v69, s[46:47]
	v_cndmask_b32_e64 v146, 0, v68, s[46:47]
	s_nop 0
	s_nop 0
	s_nop 0
	v_cmp_eq_u32_e64 s[52:53], v149, v151
	v_lshlrev_b32_e32 v149, 16, v136
	v_fma_f32 v34, v50, v149, v34
	v_lshlrev_b32_e32 v50, 16, v140
	v_fma_f32 v30, v54, v50, v212
	v_and_b32_e32 v50, 0xffff0000, v136
	v_fma_f32 v35, v51, v50, v35
	v_and_b32_e32 v50, 0xffff0000, v140
	v_fma_f32 v31, v55, v50, v213
	v_lshlrev_b32_e32 v50, 16, v135
	v_fma_f32 v36, v52, v50, v36
	v_lshlrev_b32_e32 v50, 16, v139
	v_fma_f32 v32, v56, v50, v214
	v_and_b32_e32 v50, 0xffff0000, v135
	v_fmac_f32_e32 v37, v53, v50
	v_and_b32_e32 v50, 0xffff0000, v139
	v_fmac_f32_e32 v215, v57, v50
	v_lshlrev_b32_e32 v50, 16, v134
	v_fma_f32 v26, v38, v50, v216
	v_lshlrev_b32_e32 v38, 16, v138
	v_fma_f32 v22, v220, v38, v172
	v_and_b32_e32 v38, 0xffff0000, v134
	v_fma_f32 v27, v39, v38, v217
	v_and_b32_e32 v38, 0xffff0000, v138
	v_fma_f32 v23, v221, v38, v173
	v_lshlrev_b32_e32 v38, 16, v133
	v_fma_f32 v28, v40, v38, v218
	v_lshlrev_b32_e32 v38, 16, v137
	v_fma_f32 v24, v222, v38, v174
	v_and_b32_e32 v38, 0xffff0000, v133
	v_fmac_f32_e32 v219, v41, v38
	v_and_b32_e32 v38, 0xffff0000, v137
	v_fmac_f32_e32 v175, v223, v38
	v_lshlrev_b32_e32 v38, 16, v144
	v_fmac_f32_e32 v34, v228, v38
	v_lshlrev_b32_e32 v38, 16, v148
	v_fmac_f32_e32 v30, v70, v38
	v_and_b32_e32 v38, 0xffff0000, v144
	v_fmac_f32_e32 v35, v229, v38
	v_and_b32_e32 v38, 0xffff0000, v148
	v_fmac_f32_e32 v31, v71, v38
	v_lshlrev_b32_e32 v38, 16, v143
	v_fmac_f32_e32 v36, v230, v38
	v_lshlrev_b32_e32 v38, 16, v147
	v_fmac_f32_e32 v32, v72, v38
	v_and_b32_e32 v38, 0xffff0000, v143
	v_fmac_f32_e32 v37, v231, v38
	v_and_b32_e32 v38, 0xffff0000, v147
	v_fmac_f32_e32 v215, v73, v38
	v_lshlrev_b32_e32 v38, 16, v142
	v_fmac_f32_e32 v26, v224, v38
	v_lshlrev_b32_e32 v38, 16, v146
	v_fmac_f32_e32 v22, v232, v38
	v_and_b32_e32 v38, 0xffff0000, v142
	v_fmac_f32_e32 v27, v225, v38
	v_and_b32_e32 v38, 0xffff0000, v146
	v_fmac_f32_e32 v23, v233, v38
	v_lshlrev_b32_e32 v38, 16, v141
	v_fmac_f32_e32 v28, v226, v38
	v_lshlrev_b32_e32 v38, 16, v145
	v_fmac_f32_e32 v24, v234, v38
	v_and_b32_e32 v38, 0xffff0000, v141
	v_fmac_f32_e32 v219, v227, v38
	v_and_b32_e32 v38, 0xffff0000, v145
	v_fmac_f32_e32 v175, v235, v38
	s_waitcnt vmcnt(1)
	v_cndmask_b32_e64 v86, 0, v74, s[52:53]
	s_waitcnt vmcnt(0)
	v_cndmask_b32_e64 v90, 0, v78, s[52:53]
	v_lshlrev_b32_e32 v38, 16, v86
	v_fmac_f32_e32 v34, v240, v38
	v_lshlrev_b32_e32 v38, 16, v90
	v_mov_b32_e32 v87, v75
	v_mov_b32_e32 v88, v76
	v_mov_b32_e32 v89, v77
	v_mov_b32_e32 v91, v79
	v_mov_b32_e32 v92, v80
	v_mov_b32_e32 v93, v81
	v_fmac_f32_e32 v30, v82, v38
	v_and_b32_e32 v38, 0xffff0000, v86
	v_cndmask_b32_e64 v87, 0, v87, s[52:53]
	v_fmac_f32_e32 v35, v241, v38
	v_and_b32_e32 v38, 0xffff0000, v90
	v_cndmask_b32_e64 v91, 0, v91, s[52:53]
	v_fmac_f32_e32 v31, v83, v38
	v_lshlrev_b32_e32 v38, 16, v87
	v_fmac_f32_e32 v36, v242, v38
	v_lshlrev_b32_e32 v38, 16, v91
	v_fmac_f32_e32 v32, v84, v38
	v_and_b32_e32 v38, 0xffff0000, v87
	v_cndmask_b32_e64 v88, 0, v88, s[52:53]
	v_fmac_f32_e32 v37, v243, v38
	v_and_b32_e32 v38, 0xffff0000, v91
	v_cndmask_b32_e64 v92, 0, v92, s[52:53]
	v_fmac_f32_e32 v215, v85, v38
	v_lshlrev_b32_e32 v38, 16, v88
	v_fmac_f32_e32 v26, v236, v38
	v_lshlrev_b32_e32 v38, 16, v92
	v_fmac_f32_e32 v22, v244, v38
	v_and_b32_e32 v38, 0xffff0000, v88
	v_cndmask_b32_e64 v89, 0, v89, s[52:53]
	v_fmac_f32_e32 v27, v237, v38
	v_and_b32_e32 v38, 0xffff0000, v92
	v_cndmask_b32_e64 v93, 0, v93, s[52:53]
	v_fmac_f32_e32 v23, v245, v38
	v_lshlrev_b32_e32 v38, 16, v89
	v_fmac_f32_e32 v28, v238, v38
	v_lshlrev_b32_e32 v38, 16, v93
	v_fmac_f32_e32 v24, v246, v38
	v_and_b32_e32 v38, 0xffff0000, v89
	v_fmac_f32_e32 v219, v239, v38
	v_and_b32_e32 v38, 0xffff0000, v93
	v_fmac_f32_e32 v175, v247, v38
	v_bfe_u32 v38, v30, 16, 1
	v_add3_u32 v30, v30, v38, s94
	ds_write_b16_d16_hi v101, v30 offset:2048
	v_bfe_u32 v30, v34, 16, 1
	v_add3_u32 v30, v34, v30, s94
	ds_write_b16_d16_hi v101, v30 offset:26112
	v_bfe_u32 v30, v31, 16, 1
	v_add3_u32 v30, v31, v30, s94
	ds_write_b16_d16_hi v101, v30 offset:5120
	v_bfe_u32 v30, v35, 16, 1
	v_add3_u32 v30, v35, v30, s94
	ds_write_b16_d16_hi v101, v30 offset:28160
	v_bfe_u32 v30, v32, 16, 1
	v_add3_u32 v30, v32, v30, s94
	ds_write_b16_d16_hi v101, v30 offset:8192
	v_bfe_u32 v30, v36, 16, 1
	v_add3_u32 v30, v36, v30, s94
	ds_write_b16_d16_hi v101, v30 offset:30208
	v_bfe_u32 v30, v215, 16, 1
	v_add3_u32 v30, v215, v30, s94
	ds_write_b16_d16_hi v101, v30 offset:11264
	v_bfe_u32 v30, v37, 16, 1
	v_add3_u32 v30, v37, v30, s94
	ds_write_b16_d16_hi v101, v30 offset:32256
	v_bfe_u32 v30, v22, 16, 1
	v_add3_u32 v22, v22, v30, s94
	ds_write_b16_d16_hi v101, v22 offset:14336
	v_bfe_u32 v22, v26, 16, 1
	v_add3_u32 v22, v26, v22, s94
	ds_write_b16_d16_hi v101, v22 offset:34304
	v_bfe_u32 v22, v23, 16, 1
	v_add3_u32 v22, v23, v22, s94
	ds_write_b16_d16_hi v101, v22 offset:17408
	v_bfe_u32 v22, v27, 16, 1
	v_add3_u32 v22, v27, v22, s94
	ds_write_b16_d16_hi v101, v22 offset:36352
	v_bfe_u32 v22, v24, 16, 1
	v_add3_u32 v22, v24, v22, s94
	ds_write_b16_d16_hi v101, v22 offset:20480
	v_bfe_u32 v22, v28, 16, 1
	v_add3_u32 v22, v28, v22, s94
	ds_write_b16_d16_hi v101, v22 offset:38400
	v_bfe_u32 v22, v175, 16, 1
	v_add3_u32 v22, v175, v22, s94
	ds_write_b16_d16_hi v101, v22 offset:23552
	v_bfe_u32 v22, v219, 16, 1
	v_add3_u32 v22, v219, v22, s94
	ds_write_b16_d16_hi v101, v22 offset:40448
	v_mbcnt_hi_u32_b32 v22, -1, v194
	v_and_b32_e32 v23, 64, v22
	v_add_u32_e32 v23, 64, v23
	v_xor_b32_e32 v24, 32, v22
	v_cmp_lt_i32_e32 vcc, v24, v23
	v_lshlrev_b32_e32 v79, 4, v127
	v_add_u32_e32 v65, s17, v126
	v_cndmask_b32_e32 v24, v22, v24, vcc
	v_lshlrev_b32_e32 v71, 2, v24
	v_xor_b32_e32 v24, 16, v22
	v_cmp_lt_i32_e32 vcc, v24, v23
	v_lshlrev_b32_e32 v78, 3, v128
	v_lshl_or_b32 v81, v128, 2, v79
	v_cndmask_b32_e32 v24, v22, v24, vcc
	v_lshlrev_b32_e32 v72, 2, v24
	v_xor_b32_e32 v24, 8, v22
	v_cmp_lt_i32_e32 vcc, v24, v23
	v_add_u32_e32 v70, v65, v160
	v_and_b32_e32 v80, 2, v132
	v_cndmask_b32_e32 v24, v22, v24, vcc
	v_lshlrev_b32_e32 v73, 2, v24
	v_xor_b32_e32 v24, 4, v22
	v_cmp_lt_i32_e32 vcc, v24, v23
	v_lshl_add_u32 v82, v81, 1, s17
	v_lshl_add_u64 v[62:63], s[88:89], 0, v[160:161]
	v_cndmask_b32_e32 v24, v22, v24, vcc
	v_lshlrev_b32_e32 v74, 2, v24
	v_xor_b32_e32 v24, 2, v22
	v_cmp_lt_i32_e32 vcc, v24, v23
	v_sub_u32_e32 v84, v78, v127
	s_waitcnt lgkmcnt(0)
	v_cndmask_b32_e32 v24, v22, v24, vcc
	v_lshlrev_b32_e32 v75, 2, v24
	v_xor_b32_e32 v24, 1, v22
	v_cmp_lt_i32_e32 vcc, v24, v23
	v_and_b32_e32 v23, 48, v125
	v_mov_b32_e32 v25, v175
	v_mov_b32_e32 v29, v219
	v_mov_b32_e32 v33, v215
	v_mov_b32_e32 v42, v220
	v_mov_b32_e32 v43, v221
	v_mov_b32_e32 v44, v222
	v_mov_b32_e32 v45, v223
	v_mov_b32_e32 v46, v224
	v_mov_b32_e32 v47, v225
	v_mov_b32_e32 v48, v226
	v_mov_b32_e32 v49, v227
	v_mov_b32_e32 v58, v232
	v_mov_b32_e32 v59, v233
	v_mov_b32_e32 v60, v234
	v_mov_b32_e32 v61, v235
	v_mov_b32_e32 v64, v238
	v_mov_b32_e32 v66, v228
	v_mov_b32_e32 v67, v229
	v_mov_b32_e32 v68, v230
	v_mov_b32_e32 v69, v231
	v_mov_b32_e32 v76, v246
	v_mov_b32_e32 v77, v247
	s_barrier
	v_cndmask_b32_e32 v22, v22, v24, vcc
	v_lshlrev_b32_e32 v76, 2, v22
	v_or_b32_e32 v22, v130, v129
	v_or_b32_e32 v77, 0x28000, v22
	v_or_b32_e32 v83, 0x20000, v22
	v_lshlrev_b32_e32 v22, 5, v127
	v_add3_u32 v85, v22, v23, s17
